# adds: fused HGRN2 loop fminf(z,0) without the NaN-canonicalising v_max (16 fewer VALU per chunk, identical for non-NaN)
# speedup vs baseline: 1.0039x; 1.0039x over previous
; __device__ __forceinline__ void hg_local_unit(const Params& P, LAS unsigned char* lds, int layer, int g0, int h, float* Sout, int tid, int lane, int wave) {
;     ...
;         for (int i = 0; i < 16; ++i) { const float zz = z[i]; const float e = __expf(-fabsf(zz)), r = __builtin_amdgcn_rcpf(1.f + e), er = e * r;
;             const float lf = (layer == 0) ? (fminf(zz, 0.f) - __logf(1.f + e)) : __logf(lbv + oml * (zz > 0.f ? r : er));
;             run += lf; bc[i] = run; kk[i] = oml * (zz > 0.f ? er : r); }
.LBB0_805:
	s_andn2_b64 vcc, exec, s[66:67]
	s_cbranch_vccnz .LBB0_807
	v_cmp_gt_f32_e32 vcc, s91, v58
	s_nop 1
	v_cndmask_b32_e64 v55, 0, 32, vcc
	v_ldexp_f32 v55, v58, v55
	v_log_f32_e32 v55, v55
	v_min_f32_e32 v58, 0, v42
	v_mul_f32_e32 v59, 0x3f317217, v55
	v_fma_f32 v59, v55, s29, -v59
	v_fmac_f32_e32 v59, 0x3377d1cf, v55
	v_fmac_f32_e32 v59, 0x3f317217, v55
	v_cmp_lt_f32_e64 s[64:65], |v55|, s28
	s_nop 1
	v_cndmask_b32_e64 v55, v55, v59, s[64:65]
	v_cndmask_b32_e32 v59, 0, v226, vcc
	v_sub_f32_e32 v55, v55, v59
	v_sub_f32_e32 v55, v58, v55

; __device__ __forceinline__ void hg_local_unit(const Params& P, LAS unsigned char* lds, int layer, int g0, int h, float* Sout, int tid, int lane, int wave) {
;     ...
;         for (int i = 0; i < 16; ++i) { const float zz = z[i]; const float e = __expf(-fabsf(zz)), r = __builtin_amdgcn_rcpf(1.f + e), er = e * r;
;             const float lf = (layer == 0) ? (fminf(zz, 0.f) - __logf(1.f + e)) : __logf(lbv + oml * (zz > 0.f ? r : er));
;             run += lf; bc[i] = run; kk[i] = oml * (zz > 0.f ? er : r); }
.LBB0_809:
	s_andn2_b64 vcc, exec, s[80:81]
	s_cbranch_vccnz .LBB0_811
	v_cmp_gt_f32_e32 vcc, s91, v59
	s_nop 1
	v_cndmask_b32_e64 v58, 0, 32, vcc
	v_ldexp_f32 v58, v59, v58
	v_log_f32_e32 v58, v58
	v_min_f32_e32 v59, 0, v43
	v_mul_f32_e32 v141, 0x3f317217, v58
	v_fma_f32 v141, v58, s29, -v141
	v_fmac_f32_e32 v141, 0x3377d1cf, v58
	v_fmac_f32_e32 v141, 0x3f317217, v58
	v_cmp_lt_f32_e64 s[66:67], |v58|, s28
	s_nop 1
	v_cndmask_b32_e64 v58, v58, v141, s[66:67]
	v_cndmask_b32_e32 v141, 0, v226, vcc
	v_sub_f32_e32 v58, v58, v141
	v_sub_f32_e32 v58, v59, v58

; __device__ __forceinline__ void hg_local_unit(const Params& P, LAS unsigned char* lds, int layer, int g0, int h, float* Sout, int tid, int lane, int wave) {
;     ...
;         for (int i = 0; i < 16; ++i) { const float zz = z[i]; const float e = __expf(-fabsf(zz)), r = __builtin_amdgcn_rcpf(1.f + e), er = e * r;
;             const float lf = (layer == 0) ? (fminf(zz, 0.f) - __logf(1.f + e)) : __logf(lbv + oml * (zz > 0.f ? r : er));
;             run += lf; bc[i] = run; kk[i] = oml * (zz > 0.f ? er : r); }
.LBB0_813:
	s_andn2_b64 vcc, exec, s[80:81]
	s_cbranch_vccnz .LBB0_815
	v_cmp_gt_f32_e32 vcc, s91, v141
	s_nop 1
	v_cndmask_b32_e64 v59, 0, 32, vcc
	v_ldexp_f32 v59, v141, v59
	v_log_f32_e32 v59, v59
	v_min_f32_e32 v141, 0, v56
	v_mul_f32_e32 v142, 0x3f317217, v59
	v_fma_f32 v142, v59, s29, -v142
	v_fmac_f32_e32 v142, 0x3377d1cf, v59
	v_fmac_f32_e32 v142, 0x3f317217, v59
	v_cmp_lt_f32_e64 s[66:67], |v59|, s28
	s_nop 1
	v_cndmask_b32_e64 v59, v59, v142, s[66:67]
	v_cndmask_b32_e32 v142, 0, v226, vcc
	v_sub_f32_e32 v59, v59, v142
	v_sub_f32_e32 v59, v141, v59

; __device__ __forceinline__ void hg_local_unit(const Params& P, LAS unsigned char* lds, int layer, int g0, int h, float* Sout, int tid, int lane, int wave) {
;     ...
;         for (int i = 0; i < 16; ++i) { const float zz = z[i]; const float e = __expf(-fabsf(zz)), r = __builtin_amdgcn_rcpf(1.f + e), er = e * r;
;             const float lf = (layer == 0) ? (fminf(zz, 0.f) - __logf(1.f + e)) : __logf(lbv + oml * (zz > 0.f ? r : er));
;             run += lf; bc[i] = run; kk[i] = oml * (zz > 0.f ? er : r); }
.LBB0_817:
	s_andn2_b64 vcc, exec, s[80:81]
	s_cbranch_vccnz .LBB0_819
	v_cmp_gt_f32_e32 vcc, s91, v142
	s_nop 1
	v_cndmask_b32_e64 v141, 0, 32, vcc
	v_ldexp_f32 v141, v142, v141
	v_log_f32_e32 v141, v141
	v_min_f32_e32 v142, 0, v44
	v_mul_f32_e32 v143, 0x3f317217, v141
	v_fma_f32 v143, v141, s29, -v143
	v_fmac_f32_e32 v143, 0x3377d1cf, v141
	v_fmac_f32_e32 v143, 0x3f317217, v141
	v_cmp_lt_f32_e64 s[66:67], |v141|, s28
	s_nop 1
	v_cndmask_b32_e64 v141, v141, v143, s[66:67]
	v_cndmask_b32_e32 v143, 0, v226, vcc
	v_sub_f32_e32 v141, v141, v143
	v_sub_f32_e32 v141, v142, v141

; __device__ __forceinline__ void hg_local_unit(const Params& P, LAS unsigned char* lds, int layer, int g0, int h, float* Sout, int tid, int lane, int wave) {
;     ...
;         for (int i = 0; i < 16; ++i) { const float zz = z[i]; const float e = __expf(-fabsf(zz)), r = __builtin_amdgcn_rcpf(1.f + e), er = e * r;
;             const float lf = (layer == 0) ? (fminf(zz, 0.f) - __logf(1.f + e)) : __logf(lbv + oml * (zz > 0.f ? r : er));
;             run += lf; bc[i] = run; kk[i] = oml * (zz > 0.f ? er : r); }
.LBB0_821:
	s_andn2_b64 vcc, exec, s[80:81]
	s_cbranch_vccnz .LBB0_823
	v_cmp_gt_f32_e32 vcc, s91, v143
	s_nop 1
	v_cndmask_b32_e64 v142, 0, 32, vcc
	v_ldexp_f32 v142, v143, v142
	v_log_f32_e32 v142, v142
	v_min_f32_e32 v143, 0, v57
	v_mul_f32_e32 v144, 0x3f317217, v142
	v_fma_f32 v144, v142, s29, -v144
	v_fmac_f32_e32 v144, 0x3377d1cf, v142
	v_fmac_f32_e32 v144, 0x3f317217, v142
	v_cmp_lt_f32_e64 s[66:67], |v142|, s28
	s_nop 1
	v_cndmask_b32_e64 v142, v142, v144, s[66:67]
	v_cndmask_b32_e32 v144, 0, v226, vcc
	v_sub_f32_e32 v142, v142, v144
	v_sub_f32_e32 v142, v143, v142

; __device__ __forceinline__ void hg_local_unit(const Params& P, LAS unsigned char* lds, int layer, int g0, int h, float* Sout, int tid, int lane, int wave) {
;     ...
;         for (int i = 0; i < 16; ++i) { const float zz = z[i]; const float e = __expf(-fabsf(zz)), r = __builtin_amdgcn_rcpf(1.f + e), er = e * r;
;             const float lf = (layer == 0) ? (fminf(zz, 0.f) - __logf(1.f + e)) : __logf(lbv + oml * (zz > 0.f ? r : er));
;             run += lf; bc[i] = run; kk[i] = oml * (zz > 0.f ? er : r); }
.LBB0_825:
	s_andn2_b64 vcc, exec, s[80:81]
	s_cbranch_vccnz .LBB0_827
	v_cmp_gt_f32_e32 vcc, s91, v144
	s_nop 1
	v_cndmask_b32_e64 v143, 0, 32, vcc
	v_ldexp_f32 v143, v144, v143
	v_log_f32_e32 v143, v143
	v_min_f32_e32 v144, 0, v157
	v_mul_f32_e32 v145, 0x3f317217, v143
	v_fma_f32 v145, v143, s29, -v145
	v_fmac_f32_e32 v145, 0x3377d1cf, v143
	v_fmac_f32_e32 v145, 0x3f317217, v143
	v_cmp_lt_f32_e64 s[66:67], |v143|, s28
	s_nop 1
	v_cndmask_b32_e64 v143, v143, v145, s[66:67]
	v_cndmask_b32_e32 v145, 0, v226, vcc
	v_sub_f32_e32 v143, v143, v145
	v_sub_f32_e32 v143, v144, v143

; __device__ __forceinline__ void hg_local_unit(const Params& P, LAS unsigned char* lds, int layer, int g0, int h, float* Sout, int tid, int lane, int wave) {
;     ...
;         for (int i = 0; i < 16; ++i) { const float zz = z[i]; const float e = __expf(-fabsf(zz)), r = __builtin_amdgcn_rcpf(1.f + e), er = e * r;
;             const float lf = (layer == 0) ? (fminf(zz, 0.f) - __logf(1.f + e)) : __logf(lbv + oml * (zz > 0.f ? r : er));
;             run += lf; bc[i] = run; kk[i] = oml * (zz > 0.f ? er : r); }
.LBB0_829:
	s_andn2_b64 vcc, exec, s[80:81]
	s_cbranch_vccnz .LBB0_831
	v_cmp_gt_f32_e32 vcc, s91, v145
	s_nop 1
	v_cndmask_b32_e64 v144, 0, 32, vcc
	v_ldexp_f32 v144, v145, v144
	v_log_f32_e32 v144, v144
	v_min_f32_e32 v145, 0, v48
	v_mul_f32_e32 v146, 0x3f317217, v144
	v_fma_f32 v146, v144, s29, -v146
	v_fmac_f32_e32 v146, 0x3377d1cf, v144
	v_fmac_f32_e32 v146, 0x3f317217, v144
	v_cmp_lt_f32_e64 s[66:67], |v144|, s28
	s_nop 1
	v_cndmask_b32_e64 v144, v144, v146, s[66:67]
	v_cndmask_b32_e32 v146, 0, v226, vcc
	v_sub_f32_e32 v144, v144, v146
	v_sub_f32_e32 v144, v145, v144

; __device__ __forceinline__ void hg_local_unit(const Params& P, LAS unsigned char* lds, int layer, int g0, int h, float* Sout, int tid, int lane, int wave) {
;     ...
;         for (int i = 0; i < 16; ++i) { const float zz = z[i]; const float e = __expf(-fabsf(zz)), r = __builtin_amdgcn_rcpf(1.f + e), er = e * r;
;             const float lf = (layer == 0) ? (fminf(zz, 0.f) - __logf(1.f + e)) : __logf(lbv + oml * (zz > 0.f ? r : er));
;             run += lf; bc[i] = run; kk[i] = oml * (zz > 0.f ? er : r); }
.LBB0_833:
	s_andn2_b64 vcc, exec, s[80:81]
	s_cbranch_vccnz .LBB0_835
	v_cmp_gt_f32_e32 vcc, s91, v146
	s_nop 1
	v_cndmask_b32_e64 v145, 0, 32, vcc
	v_ldexp_f32 v145, v146, v145
	v_log_f32_e32 v145, v145
	v_min_f32_e32 v146, 0, v45
	v_mul_f32_e32 v147, 0x3f317217, v145
	v_fma_f32 v147, v145, s29, -v147
	v_fmac_f32_e32 v147, 0x3377d1cf, v145
	v_fmac_f32_e32 v147, 0x3f317217, v145
	v_cmp_lt_f32_e64 s[66:67], |v145|, s28
	s_nop 1
	v_cndmask_b32_e64 v145, v145, v147, s[66:67]
	v_cndmask_b32_e32 v147, 0, v226, vcc
	v_sub_f32_e32 v145, v145, v147
	v_sub_f32_e32 v145, v146, v145

; __device__ __forceinline__ void hg_local_unit(const Params& P, LAS unsigned char* lds, int layer, int g0, int h, float* Sout, int tid, int lane, int wave) {
;     ...
;         for (int i = 0; i < 16; ++i) { const float zz = z[i]; const float e = __expf(-fabsf(zz)), r = __builtin_amdgcn_rcpf(1.f + e), er = e * r;
;             const float lf = (layer == 0) ? (fminf(zz, 0.f) - __logf(1.f + e)) : __logf(lbv + oml * (zz > 0.f ? r : er));
;             run += lf; bc[i] = run; kk[i] = oml * (zz > 0.f ? er : r); }
.LBB0_837:
	s_andn2_b64 vcc, exec, s[80:81]
	s_cbranch_vccnz .LBB0_839
	v_cmp_gt_f32_e32 vcc, s91, v147
	s_nop 1
	v_cndmask_b32_e64 v146, 0, 32, vcc
	v_ldexp_f32 v146, v147, v146
	v_log_f32_e32 v146, v146
	v_min_f32_e32 v147, 0, v52
	v_mul_f32_e32 v148, 0x3f317217, v146
	v_fma_f32 v148, v146, s29, -v148
	v_fmac_f32_e32 v148, 0x3377d1cf, v146
	v_fmac_f32_e32 v148, 0x3f317217, v146
	v_cmp_lt_f32_e64 s[66:67], |v146|, s28
	s_nop 1
	v_cndmask_b32_e64 v146, v146, v148, s[66:67]
	v_cndmask_b32_e32 v148, 0, v226, vcc
	v_sub_f32_e32 v146, v146, v148
	v_sub_f32_e32 v146, v147, v146

; __device__ __forceinline__ void hg_local_unit(const Params& P, LAS unsigned char* lds, int layer, int g0, int h, float* Sout, int tid, int lane, int wave) {
;     ...
;         for (int i = 0; i < 16; ++i) { const float zz = z[i]; const float e = __expf(-fabsf(zz)), r = __builtin_amdgcn_rcpf(1.f + e), er = e * r;
;             const float lf = (layer == 0) ? (fminf(zz, 0.f) - __logf(1.f + e)) : __logf(lbv + oml * (zz > 0.f ? r : er));
;             run += lf; bc[i] = run; kk[i] = oml * (zz > 0.f ? er : r); }
.LBB0_841:
	s_andn2_b64 vcc, exec, s[80:81]
	s_cbranch_vccnz .LBB0_843
	v_cmp_gt_f32_e32 vcc, s91, v148
	s_nop 1
	v_cndmask_b32_e64 v147, 0, 32, vcc
	v_ldexp_f32 v147, v148, v147
	v_log_f32_e32 v147, v147
	v_min_f32_e32 v148, 0, v53
	v_mul_f32_e32 v149, 0x3f317217, v147
	v_fma_f32 v149, v147, s29, -v149
	v_fmac_f32_e32 v149, 0x3377d1cf, v147
	v_fmac_f32_e32 v149, 0x3f317217, v147
	v_cmp_lt_f32_e64 s[66:67], |v147|, s28
	s_nop 1
	v_cndmask_b32_e64 v147, v147, v149, s[66:67]
	v_cndmask_b32_e32 v149, 0, v226, vcc
	v_sub_f32_e32 v147, v147, v149
	v_sub_f32_e32 v147, v148, v147

; __device__ __forceinline__ void hg_local_unit(const Params& P, LAS unsigned char* lds, int layer, int g0, int h, float* Sout, int tid, int lane, int wave) {
;     ...
;         for (int i = 0; i < 16; ++i) { const float zz = z[i]; const float e = __expf(-fabsf(zz)), r = __builtin_amdgcn_rcpf(1.f + e), er = e * r;
;             const float lf = (layer == 0) ? (fminf(zz, 0.f) - __logf(1.f + e)) : __logf(lbv + oml * (zz > 0.f ? r : er));
;             run += lf; bc[i] = run; kk[i] = oml * (zz > 0.f ? er : r); }
.LBB0_845:
	s_andn2_b64 vcc, exec, s[80:81]
	s_cbranch_vccnz .LBB0_847
	v_cmp_gt_f32_e32 vcc, s91, v149
	s_nop 1
	v_cndmask_b32_e64 v148, 0, 32, vcc
	v_ldexp_f32 v148, v149, v148
	v_log_f32_e32 v148, v148
	v_min_f32_e32 v149, 0, v54
	v_mul_f32_e32 v150, 0x3f317217, v148
	v_fma_f32 v150, v148, s29, -v150
	v_fmac_f32_e32 v150, 0x3377d1cf, v148
	v_fmac_f32_e32 v150, 0x3f317217, v148
	v_cmp_lt_f32_e64 s[66:67], |v148|, s28
	s_nop 1
	v_cndmask_b32_e64 v148, v148, v150, s[66:67]
	v_cndmask_b32_e32 v150, 0, v226, vcc
	v_sub_f32_e32 v148, v148, v150
	v_sub_f32_e32 v148, v149, v148

; __device__ __forceinline__ void hg_local_unit(const Params& P, LAS unsigned char* lds, int layer, int g0, int h, float* Sout, int tid, int lane, int wave) {
;     ...
;         for (int i = 0; i < 16; ++i) { const float zz = z[i]; const float e = __expf(-fabsf(zz)), r = __builtin_amdgcn_rcpf(1.f + e), er = e * r;
;             const float lf = (layer == 0) ? (fminf(zz, 0.f) - __logf(1.f + e)) : __logf(lbv + oml * (zz > 0.f ? r : er));
;             run += lf; bc[i] = run; kk[i] = oml * (zz > 0.f ? er : r); }
.LBB0_849:
	s_andn2_b64 vcc, exec, s[80:81]
	s_cbranch_vccnz .LBB0_851
	v_cmp_gt_f32_e32 vcc, s91, v150
	s_nop 1
	v_cndmask_b32_e64 v149, 0, 32, vcc
	v_ldexp_f32 v149, v150, v149
	v_log_f32_e32 v149, v149
	v_min_f32_e32 v150, 0, v49
	v_mul_f32_e32 v151, 0x3f317217, v149
	v_fma_f32 v151, v149, s29, -v151
	v_fmac_f32_e32 v151, 0x3377d1cf, v149
	v_fmac_f32_e32 v151, 0x3f317217, v149
	v_cmp_lt_f32_e64 s[66:67], |v149|, s28
	s_nop 1
	v_cndmask_b32_e64 v149, v149, v151, s[66:67]
	v_cndmask_b32_e32 v151, 0, v226, vcc
	v_sub_f32_e32 v149, v149, v151
	v_sub_f32_e32 v149, v150, v149

; __device__ __forceinline__ void hg_local_unit(const Params& P, LAS unsigned char* lds, int layer, int g0, int h, float* Sout, int tid, int lane, int wave) {
;     ...
;         for (int i = 0; i < 16; ++i) { const float zz = z[i]; const float e = __expf(-fabsf(zz)), r = __builtin_amdgcn_rcpf(1.f + e), er = e * r;
;             const float lf = (layer == 0) ? (fminf(zz, 0.f) - __logf(1.f + e)) : __logf(lbv + oml * (zz > 0.f ? r : er));
;             run += lf; bc[i] = run; kk[i] = oml * (zz > 0.f ? er : r); }
.LBB0_853:
	s_andn2_b64 vcc, exec, s[80:81]
	s_cbranch_vccnz .LBB0_855
	v_cmp_gt_f32_e32 vcc, s91, v151
	s_nop 1
	v_cndmask_b32_e64 v150, 0, 32, vcc
	v_ldexp_f32 v150, v151, v150
	v_log_f32_e32 v150, v150
	v_min_f32_e32 v151, 0, v50
	v_mul_f32_e32 v152, 0x3f317217, v150
	v_fma_f32 v152, v150, s29, -v152
	v_fmac_f32_e32 v152, 0x3377d1cf, v150
	v_fmac_f32_e32 v152, 0x3f317217, v150
	v_cmp_lt_f32_e64 s[66:67], |v150|, s28
	s_nop 1
	v_cndmask_b32_e64 v150, v150, v152, s[66:67]
	v_cndmask_b32_e32 v152, 0, v226, vcc
	v_sub_f32_e32 v150, v150, v152
	v_sub_f32_e32 v150, v151, v150

; __device__ __forceinline__ void hg_local_unit(const Params& P, LAS unsigned char* lds, int layer, int g0, int h, float* Sout, int tid, int lane, int wave) {
;     ...
;         for (int i = 0; i < 16; ++i) { const float zz = z[i]; const float e = __expf(-fabsf(zz)), r = __builtin_amdgcn_rcpf(1.f + e), er = e * r;
;             const float lf = (layer == 0) ? (fminf(zz, 0.f) - __logf(1.f + e)) : __logf(lbv + oml * (zz > 0.f ? r : er));
;             run += lf; bc[i] = run; kk[i] = oml * (zz > 0.f ? er : r); }
.LBB0_857:
	s_andn2_b64 vcc, exec, s[80:81]
	s_cbranch_vccnz .LBB0_859
	v_cmp_gt_f32_e32 vcc, s91, v152
	s_nop 1
	v_cndmask_b32_e64 v151, 0, 32, vcc
	v_ldexp_f32 v151, v152, v151
	v_log_f32_e32 v151, v151
	v_min_f32_e32 v152, 0, v51
	v_mul_f32_e32 v153, 0x3f317217, v151
	v_fma_f32 v153, v151, s29, -v153
	v_fmac_f32_e32 v153, 0x3377d1cf, v151
	v_fmac_f32_e32 v153, 0x3f317217, v151
	v_cmp_lt_f32_e64 s[66:67], |v151|, s28
	s_nop 1
	v_cndmask_b32_e64 v151, v151, v153, s[66:67]
	v_cndmask_b32_e32 v153, 0, v226, vcc
	v_sub_f32_e32 v151, v151, v153
	v_sub_f32_e32 v151, v152, v151

; __device__ __forceinline__ void hg_local_unit(const Params& P, LAS unsigned char* lds, int layer, int g0, int h, float* Sout, int tid, int lane, int wave) {
;     ...
;         for (int i = 0; i < 16; ++i) { const float zz = z[i]; const float e = __expf(-fabsf(zz)), r = __builtin_amdgcn_rcpf(1.f + e), er = e * r;
;             const float lf = (layer == 0) ? (fminf(zz, 0.f) - __logf(1.f + e)) : __logf(lbv + oml * (zz > 0.f ? r : er));
;             run += lf; bc[i] = run; kk[i] = oml * (zz > 0.f ? er : r); }
.LBB0_861:
	s_andn2_b64 vcc, exec, s[80:81]
	s_cbranch_vccnz .LBB0_863
	v_cmp_gt_f32_e32 vcc, s91, v153
	s_nop 1
	v_cndmask_b32_e64 v152, 0, 32, vcc
	v_ldexp_f32 v152, v153, v152
	v_log_f32_e32 v152, v152
	v_min_f32_e32 v153, 0, v46
	v_mul_f32_e32 v154, 0x3f317217, v152
	v_fma_f32 v154, v152, s29, -v154
	v_fmac_f32_e32 v154, 0x3377d1cf, v152
	v_fmac_f32_e32 v154, 0x3f317217, v152
	v_cmp_lt_f32_e64 s[66:67], |v152|, s28
	s_nop 1
	v_cndmask_b32_e64 v152, v152, v154, s[66:67]
	v_cndmask_b32_e32 v154, 0, v226, vcc
	v_sub_f32_e32 v152, v152, v154
	v_sub_f32_e32 v152, v153, v152

; __device__ __forceinline__ void hg_local_unit(const Params& P, LAS unsigned char* lds, int layer, int g0, int h, float* Sout, int tid, int lane, int wave) {
;     ...
;         for (int i = 0; i < 16; ++i) { const float zz = z[i]; const float e = __expf(-fabsf(zz)), r = __builtin_amdgcn_rcpf(1.f + e), er = e * r;
;             const float lf = (layer == 0) ? (fminf(zz, 0.f) - __logf(1.f + e)) : __logf(lbv + oml * (zz > 0.f ? r : er));
;             run += lf; bc[i] = run; kk[i] = oml * (zz > 0.f ? er : r); }
.LBB0_865:
	s_andn2_b64 vcc, exec, s[66:67]
	s_cbranch_vccnz .LBB0_867
	v_cmp_gt_f32_e32 vcc, s91, v153
	s_nop 1
	v_cndmask_b32_e64 v154, 0, 32, vcc
	v_ldexp_f32 v153, v153, v154
	v_log_f32_e32 v153, v153
	v_min_f32_e32 v154, 0, v47
	v_mul_f32_e32 v155, 0x3f317217, v153
	v_fma_f32 v155, v153, s29, -v155
	v_fmac_f32_e32 v155, 0x3377d1cf, v153
	v_fmac_f32_e32 v155, 0x3f317217, v153
	v_cmp_lt_f32_e64 s[64:65], |v153|, s28
	s_nop 1
	v_cndmask_b32_e64 v153, v153, v155, s[64:65]
	v_cndmask_b32_e32 v155, 0, v226, vcc
	v_sub_f32_e32 v153, v153, v155
	v_sub_f32_e32 v154, v154, v153
